# hot loop heads (attention, FFT x2, B K-loop, w3) aligned to 64 bytes
# baseline (speedup 1.0000x reference)
; #define LAS __attribute__((address_space(3)))
; __device__ __forceinline__ void attn_unit(const Params& p, int l, int b, int h, int qpos0, int kbeg, int nkt, int grow0, float lam, float lam_init, unsigned char* lds, int wid0) {
;     ...
;     const bf16* kt_g = K + (size_t)bh * 132 * 8192 + (size_t)(2 * wid) * 512 + lane * 8; const bf16* vt_g = Vt + (size_t)bh * 132 * 8192 + (size_t)(2 * wid) * 512 + lane * 8;
;     ...
;     const int kt0 = kbeg >> 6;
;     ...
;     const LAS unsigned char* kl_ = ldsl + ((map * 8 + hi) * 64 + r32) * 16; const LAS unsigned char* vl_ = ldsl + 16384 + (hi * 128 + r32) * 16;
;     AT_DMA(kt0, 0); if (nkt > 1) AT_DMA(kt0 + 1, 1); if (nkt > 2) AT_DMA(kt0 + 2, 2);
;     { const bf16* qp = Q + ((size_t)(bh * 2 + map) * KEYS + qpos0 + qg * 32 + r32) * 64 + hi * 8;
; #pragma unroll
;         for (int s = 0; s < 4; ++s) qf[s] = *(const bf16x8*)(qp + 16 * s);
;         float nA = sumsq8(qf[0]) + sumsq8(qf[1]), nB = sumsq8(qf[2]) + sumsq8(qf[3]);
;         nA += __shfl_xor(nA, 32); nB += __shfl_xor(nB, 32);
;         const float kA = __uint_as_float(kmax[(bh * 2 + map) * 2 + 0]), kB = __uint_as_float(kmax[(bh * 2 + map) * 2 + 1]);
;         Msh = sqrtf(nA * kA) + sqrtf(nB * kB); }
.LBB0_176:
	s_lshl_b32 s63, s62, 7
	s_cmp_lt_i32 s62, 64
	s_cselect_b64 s[46:47], -1, 0
	v_mbcnt_lo_u32_b32 v96, -1, 0
	v_mbcnt_hi_u32_b32 v96, -1, v96
	s_and_b64 s[0:1], s[46:47], exec
	v_lshlrev_b32_e32 v0, 3, v96
	v_ashrrev_i32_e32 v1, 31, v0
	s_cselect_b32 s72, 0, 0x80
	v_lshlrev_b64 v[122:123], 1, v[0:1]
	s_cselect_b32 s64, 0x84, 4
	v_lshl_add_u64 v[132:133], s[38:39], 0, v[122:123]
	s_lshl_b32 s54, s72, 14
	s_mov_b32 s55, s92
	s_mov_b32 m0, s31
	v_lshl_add_u64 v[0:1], v[132:133], 0, s[54:55]
	v_lshl_add_u64 v[134:135], s[40:41], 0, v[122:123]
	global_load_lds_dwordx4 v[0:1], off
	v_lshl_add_u64 v[0:1], v[0:1], 0, s[36:37]
	s_add_i32 m0, s31, 0x400
	v_lshl_add_u64 v[2:3], v[134:135], 0, s[54:55]
	global_load_lds_dwordx4 v[0:1], off
	s_add_i32 m0, s31, 0x4000
	v_readlane_b32 s0, v253, 62
	global_load_lds_dwordx4 v[2:3], off
	v_lshl_add_u64 v[0:1], v[2:3], 0, s[36:37]
	s_mov_b32 m0, s0
	s_or_b32 s0, s54, 0x4000
	s_mov_b32 s1, s92
	global_load_lds_dwordx4 v[0:1], off
	v_lshl_add_u64 v[0:1], v[132:133], 0, s[0:1]
	v_lshl_add_u64 v[2:3], v[134:135], 0, s[0:1]
	s_add_i32 m0, s31, 0x8000
	v_readlane_b32 s0, v253, 63
	global_load_lds_dwordx4 v[0:1], off
	v_lshl_add_u64 v[0:1], v[0:1], 0, s[36:37]
	s_mov_b32 m0, s0
	s_or_b32 s0, s54, 0x8000
	global_load_lds_dwordx4 v[0:1], off
	s_add_i32 m0, s31, 0xc000
	v_lshl_add_u64 v[0:1], v[2:3], 0, s[36:37]
	global_load_lds_dwordx4 v[2:3], off
	s_mov_b32 m0, s81
	v_lshl_add_u64 v[2:3], v[134:135], 0, s[0:1]
	global_load_lds_dwordx4 v[0:1], off
	v_lshl_add_u64 v[0:1], v[132:133], 0, s[0:1]
	s_add_i32 m0, s85, 0x10000
	s_ashr_i32 s0, s63, 31
	global_load_lds_dwordx4 v[0:1], off
	v_lshl_add_u64 v[0:1], v[0:1], 0, s[36:37]
	s_add_i32 m0, s85, 0x10400
	v_and_b32_e32 v130, 31, v96
	global_load_lds_dwordx4 v[0:1], off
	s_add_i32 m0, s85, 0x14000
	v_ashrrev_i32_e32 v131, 5, v96
	global_load_lds_dwordx4 v[2:3], off
	s_add_i32 m0, s85, 0x14400
	s_add_u32 s1, s58, s63
	s_addc_u32 s0, s59, s0
	v_or_b32_e32 v0, s1, v130
	v_mov_b32_e32 v1, s0
	v_readlane_b32 s0, v252, 22
	v_lshlrev_b64 v[0:1], 7, v[0:1]
	v_readlane_b32 s1, v252, 23
	v_lshlrev_b32_e32 v4, 3, v131
	v_ashrrev_i32_e32 v5, 31, v4
	v_lshl_add_u64 v[0:1], s[0:1], 0, v[0:1]
	v_lshl_add_u64 v[0:1], v[4:5], 1, v[0:1]
	global_load_dwordx4 v[102:105], v[0:1], off offset:32
	global_load_dwordx4 v[110:113], v[0:1], off
	global_load_dwordx4 v[98:101], v[0:1], off offset:96
	global_load_dwordx4 v[106:109], v[0:1], off offset:64
	s_nop 0
	global_load_dwordx2 v[0:1], v97, s[42:43]
	v_readlane_b32 s0, v252, 12
	v_lshl_add_u64 v[2:3], v[2:3], 0, s[36:37]
	global_load_lds_dwordx4 v[2:3], off
	v_lshl_add_u32 v4, v131, 6, s0
	v_or_b32_e32 v24, v4, v130
	s_mov_b32 s4, 0xf800000
	v_lshl_add_u32 v138, v24, 4, 0
	s_waitcnt vmcnt(0)
	s_waitcnt vmcnt(0) lgkmcnt(0)
	s_barrier
	s_mov_b32 s82, 0
	s_mov_b32 s74, 1
	s_mov_b32 s65, 0x8000
	s_mov_b32 s55, 0x10000
	s_add_i32 s73, s64, -3
	s_or_b32 s72, s72, 3
	v_and_b32_e32 v7, 0xffff0000, v102
	v_and_b32_e32 v6, 0xffff0000, v110
	v_lshlrev_b32_e32 v5, 16, v102
	v_lshlrev_b32_e32 v4, 16, v110
	v_pk_mul_f32 v[6:7], v[6:7], v[6:7]
	v_lshlrev_b32_e32 v9, 16, v103
	v_lshlrev_b32_e32 v8, 16, v111
	v_pk_fma_f32 v[4:5], v[4:5], v[4:5], v[6:7]
	v_and_b32_e32 v11, 0xffff0000, v103
	v_and_b32_e32 v10, 0xffff0000, v111
	v_pk_fma_f32 v[4:5], v[8:9], v[8:9], v[4:5]
	v_lshlrev_b32_e32 v13, 16, v104
	v_lshlrev_b32_e32 v12, 16, v112
	v_pk_fma_f32 v[4:5], v[10:11], v[10:11], v[4:5]
	v_and_b32_e32 v15, 0xffff0000, v104
	v_and_b32_e32 v14, 0xffff0000, v112
	v_pk_fma_f32 v[4:5], v[12:13], v[12:13], v[4:5]
	v_lshlrev_b32_e32 v17, 16, v105
	v_lshlrev_b32_e32 v16, 16, v113
	v_pk_fma_f32 v[4:5], v[14:15], v[14:15], v[4:5]
	v_and_b32_e32 v19, 0xffff0000, v105
	v_and_b32_e32 v18, 0xffff0000, v113
	v_and_b32_e32 v23, 0xffff0000, v98
	v_and_b32_e32 v22, 0xffff0000, v106
	v_pk_fma_f32 v[4:5], v[16:17], v[16:17], v[4:5]
	v_lshlrev_b32_e32 v21, 16, v98
	v_lshlrev_b32_e32 v20, 16, v106
	v_pk_mul_f32 v[22:23], v[22:23], v[22:23]
	v_pk_fma_f32 v[4:5], v[18:19], v[18:19], v[4:5]
	v_pk_fma_f32 v[6:7], v[20:21], v[20:21], v[22:23]
	v_add_f32_e32 v8, v4, v5
	v_lshlrev_b32_e32 v5, 16, v99
	v_lshlrev_b32_e32 v4, 16, v107
	v_pk_fma_f32 v[4:5], v[4:5], v[4:5], v[6:7]
	v_and_b32_e32 v7, 0xffff0000, v99
	v_and_b32_e32 v6, 0xffff0000, v107
	v_pk_fma_f32 v[4:5], v[6:7], v[6:7], v[4:5]
	v_lshlrev_b32_e32 v7, 16, v100
	v_lshlrev_b32_e32 v6, 16, v108
	ds_bpermute_b32 v9, v230, v8
	v_pk_fma_f32 v[4:5], v[6:7], v[6:7], v[4:5]
	v_and_b32_e32 v7, 0xffff0000, v100
	v_and_b32_e32 v6, 0xffff0000, v108
	v_pk_fma_f32 v[4:5], v[6:7], v[6:7], v[4:5]
	v_lshlrev_b32_e32 v7, 16, v101
	v_lshlrev_b32_e32 v6, 16, v109
	v_pk_fma_f32 v[4:5], v[6:7], v[6:7], v[4:5]
	v_and_b32_e32 v7, 0xffff0000, v101
	v_and_b32_e32 v6, 0xffff0000, v109
	v_pk_fma_f32 v[4:5], v[6:7], v[6:7], v[4:5]
	s_nop 0
	v_add_f32_e32 v4, v4, v5
	s_waitcnt lgkmcnt(0)
	v_add_f32_e32 v5, v8, v9
	v_mul_f32_e32 v0, v0, v5
	v_mul_f32_e32 v5, 0x4f800000, v0
	v_cmp_gt_f32_e32 vcc, s4, v0
	ds_bpermute_b32 v6, v230, v4
	s_waitcnt lgkmcnt(0)
; #define AT_LDK(bufoff, kbi) do { _Pragma("unroll") for (int s_ = 0; s_ < 4; ++s_) kf[s_] = *(const LAS bf16x8*)(kl_ + (bufoff) + ((2 * s_) * 64 + 32 * (kbi)) * 16); } while (0)
; #define AT_LDV(bufoff, kbi) do { _Pragma("unroll") for (int db_ = 0; db_ < 4; ++db_) { vf[2 * db_] = *(const LAS bf16x8*)(vl_ + (bufoff) + ((4 * (kbi)) * 128 + 32 * db_) * 16); vf[2 * db_ + 1] = *(const LAS bf16x8*)(vl_ + (bufoff) + ((4 * (kbi) + 2) * 128 + 32 * db_) * 16); } } while (0)
; #define AT_MQK(dst) do { dst = __builtin_amdgcn_mfma_f32_32x32x16_bf16(kf[0], qf[0], negm, 0, 0, 0); _Pragma("unroll") for (int s_ = 1; s_ < 4; ++s_) dst = __builtin_amdgcn_mfma_f32_32x32x16_bf16(kf[s_], qf[s_], dst, 0, 0, 0); } while (0)
; #define AT_MPV(pk0_, pk1_) do { _Pragma("unroll") for (int db_ = 0; db_ < 4; ++db_) { o[db_] = __builtin_amdgcn_mfma_f32_32x32x16_bf16(pk0_, vf[2 * db_], o[db_], 0, 0, 0); o[db_] = __builtin_amdgcn_mfma_f32_32x32x16_bf16(pk1_, vf[2 * db_ + 1], o[db_], 0, 0, 0); } } while (0)
; #define AT_SM(src, pk0_, pk1_) do { float ls_ = 0.f; _Pragma("unroll") for (int r_ = 0; r_ < 16; ++r_) { src[r_] = __builtin_amdgcn_exp2f(src[r_]); ls_ += src[r_]; } lsum += ls_; pk0_ = pack8(src, 0); pk1_ = pack8(src, 8); } while (0)
; #define AT_SB() __builtin_amdgcn_sched_barrier(0)
; __device__ __forceinline__ void attn_unit(const Params& p, int l, int b, int h, int qpos0, int kbeg, int nkt, int grow0, float lam, float lam_init, unsigned char* lds, int wid0) {
;     ...
;         Msh = sqrtf(nA * kA) + sqrtf(nB * kB); }
;     asm volatile("s_waitcnt vmcnt(0)" ::: "memory"); __syncthreads();
;     f32x16 Sc, Sn, negm; bf16x8 kf[4], vf[8];
; #pragma unroll
;     for (int r = 0; r < 16; ++r) negm[r] = -Msh;
;     asm volatile("" : "+v"(negm));
;     AT_LDK(0, 0); AT_MQK(Sc);
;     bf16x8 pA0, pA1, pB0, pB1;
; #pragma unroll
;     for (int j = 0; j < 8; ++j) { pA0[j] = 0; pA1[j] = 0; }
;     int bop = 98304, bo = 0, bo1 = 32768, bo2 = 65536;
;     for (int it = 0; it < nkt; ++it) {
;         AT_LDK(bo, 1); AT_LDV((it ? bop : bo), 1); AT_SB();
;         AT_SM(Sc, pB0, pB1); AT_SB();
;         __builtin_amdgcn_s_setprio(3); AT_MQK(Sn); AT_MPV(pA0, pA1); __builtin_amdgcn_s_setprio(0); AT_SB();
	v_add_f32_e32 v2, v4, v6
	v_cndmask_b32_e32 v0, v0, v5, vcc
	v_sqrt_f32_e32 v5, v0
	v_mul_f32_e32 v1, v1, v2
	v_mul_f32_e32 v2, 0x4f800000, v1
	v_add_u32_e32 v3, -1, v5
	v_fma_f32 v4, -v3, v5, v0
	v_cmp_ge_f32_e64 s[0:1], 0, v4
	v_add_u32_e32 v4, 1, v5
	s_nop 0
	v_cndmask_b32_e64 v3, v5, v3, s[0:1]
	v_fma_f32 v5, -v4, v5, v0
	v_cmp_lt_f32_e64 s[0:1], 0, v5
	s_nop 1
	v_cndmask_b32_e64 v3, v3, v4, s[0:1]
	v_cmp_gt_f32_e64 s[0:1], s4, v1
	v_mul_f32_e32 v4, 0x37800000, v3
	v_cndmask_b32_e32 v3, v3, v4, vcc
	v_cndmask_b32_e64 v1, v1, v2, s[0:1]
	v_sqrt_f32_e32 v2, v1
	v_cmp_class_f32_e32 vcc, v0, v212
	s_nop 1
	v_cndmask_b32_e32 v0, v3, v0, vcc
	v_add_u32_e32 v3, -1, v2
	v_fma_f32 v4, -v3, v2, v1
	v_cmp_ge_f32_e32 vcc, 0, v4
	v_add_u32_e32 v4, 1, v2
	s_nop 0
	v_cndmask_b32_e32 v3, v2, v3, vcc
	v_fma_f32 v2, -v4, v2, v1
	v_cmp_lt_f32_e32 vcc, 0, v2
	s_nop 1
	v_cndmask_b32_e32 v2, v3, v4, vcc
	v_mul_f32_e32 v3, 0x37800000, v2
	v_cndmask_b32_e64 v2, v2, v3, s[0:1]
	v_cmp_class_f32_e32 vcc, v1, v212
	s_nop 1
	v_cndmask_b32_e32 v1, v2, v1, vcc
	v_add_f32_e32 v0, v0, v1
	v_xor_b32_e32 v64, 0x80000000, v0
	v_mov_b32_e32 v65, v64
	v_mov_b32_e32 v66, v64
	v_mov_b32_e32 v67, v64
	v_mov_b32_e32 v68, v64
	v_mov_b32_e32 v69, v64
	v_mov_b32_e32 v70, v64
	v_mov_b32_e32 v71, v64
	v_mov_b32_e32 v72, v64
	v_mov_b32_e32 v73, v64
	v_mov_b32_e32 v74, v64
	v_mov_b32_e32 v75, v64
	v_mov_b32_e32 v76, v64
	v_mov_b32_e32 v77, v64
	v_mov_b32_e32 v78, v64
	v_mov_b32_e32 v79, v64
	ds_read_b128 v[16:19], v138
	ds_read_b128 v[20:23], v138 offset:512
	s_waitcnt lgkmcnt(1)
	v_mfma_f32_32x32x16_bf16 v[0:15], v[16:19], v[110:113], v[64:79]
	ds_read_b128 v[16:19], v138 offset:2048
	ds_read_b128 v[24:27], v138 offset:4096
	ds_read_b128 v[32:35], v138 offset:2560
	ds_read_b128 v[36:39], v138 offset:4608
	s_waitcnt lgkmcnt(3)
	v_mfma_f32_32x32x16_bf16 v[0:15], v[16:19], v[102:105], v[0:15]
	v_lshlrev_b32_e32 v16, 11, v131
	v_lshlrev_b32_e32 v17, 4, v130
	v_add3_u32 v142, 0, v16, v17
	s_waitcnt lgkmcnt(2)
	v_mfma_f32_32x32x16_bf16 v[0:15], v[24:27], v[106:109], v[0:15]
	ds_read_b128 v[16:19], v138 offset:6144
	ds_read_b128 v[40:43], v138 offset:6656
	ds_read_b128 v[24:27], v142 offset:24576
	ds_read_b128 v[28:31], v142 offset:25088
	ds_read_b128 v[44:47], v142 offset:28672
	ds_read_b128 v[48:51], v142 offset:29184
	ds_read_b128 v[52:55], v142 offset:25600
	ds_read_b128 v[56:59], v142 offset:26112
	ds_read_b128 v[60:63], v142 offset:29696
	ds_read_b128 v[114:117], v142 offset:30208
	s_waitcnt lgkmcnt(9)
	v_mfma_f32_32x32x16_bf16 v[0:15], v[16:19], v[98:101], v[0:15]
	s_nop 11
	v_exp_f32_e32 v136, v1
	s_lshl_b32 s0, s72, 14
	s_mov_b32 s1, s92
	v_lshl_add_u64 v[148:149], v[134:135], 0, s[0:1]
	v_lshl_add_u64 v[152:153], v[132:133], 0, s[0:1]
	v_exp_f32_e32 v128, v0
	v_exp_f32_e32 v140, v2
	v_exp_f32_e32 v196, v3
	v_exp_f32_e32 v198, v4
	v_exp_f32_e32 v200, v5
	v_exp_f32_e32 v202, v6
	v_exp_f32_e32 v204, v7
	v_exp_f32_e32 v234, v8
	v_exp_f32_e32 v236, v9
	v_exp_f32_e32 v238, v10
	v_exp_f32_e32 v240, v11
	v_exp_f32_e32 v242, v12
	v_exp_f32_e32 v244, v13
	v_exp_f32_e32 v246, v14
	v_exp_f32_e32 v248, v15
	v_lshl_add_u64 v[150:151], v[148:149], 0, s[36:37]
	v_lshl_add_u64 v[154:155], v[152:153], 0, s[36:37]
	v_cvt_pk_bf16_f32 v124, v128, v136
	v_cvt_pk_bf16_f32 v125, v140, v196
	v_cvt_pk_bf16_f32 v126, v198, v200
	v_cvt_pk_bf16_f32 v127, v202, v204
	v_cvt_pk_bf16_f32 v144, v234, v236
	v_cvt_pk_bf16_f32 v145, v238, v240
	v_cvt_pk_bf16_f32 v146, v242, v244
	v_cvt_pk_bf16_f32 v147, v246, v248
	s_setprio 3
	v_mfma_f32_32x32x16_bf16 v[80:95], v[20:23], v[110:113], v[64:79]
	s_mov_b32 s94, s92
	s_mov_b32 s95, s92
	s_mov_b32 s93, s92
	v_mov_b64_e32 v[120:121], s[94:95]
	v_mov_b64_e32 v[118:119], s[92:93]
	v_mfma_f32_32x32x16_bf16 v[80:95], v[32:35], v[102:105], v[80:95]
	v_mfma_f32_32x32x16_bf16 v[80:95], v[36:39], v[106:109], v[80:95]
	s_waitcnt lgkmcnt(8)
	v_mfma_f32_32x32x16_bf16 v[80:95], v[40:43], v[98:101], v[80:95]
	s_waitcnt lgkmcnt(7)
	v_mfma_f32_32x32x16_bf16 v[0:15], v[118:121], v[24:27], 0
	s_nop 9
	v_exp_f32_e32 v129, v80
	v_exp_f32_e32 v137, v81
	v_exp_f32_e32 v141, v82
	v_exp_f32_e32 v197, v83
	v_pk_add_f32 v[32:33], v[128:129], 0 op_sel_hi:[1,0]
	v_exp_f32_e32 v199, v84
	v_pk_add_f32 v[32:33], v[136:137], v[32:33]
	s_waitcnt lgkmcnt(6)
	v_mfma_f32_32x32x16_bf16 v[16:31], v[118:121], v[28:31], 0
	v_exp_f32_e32 v201, v85
	v_pk_add_f32 v[32:33], v[140:141], v[32:33]
	v_exp_f32_e32 v203, v86
	v_exp_f32_e32 v205, v87
	v_exp_f32_e32 v235, v88
	v_exp_f32_e32 v237, v89
	v_exp_f32_e32 v239, v90
	s_waitcnt lgkmcnt(5)
	v_mfma_f32_32x32x16_bf16 v[0:15], v[118:121], v[44:47], v[0:15]
	v_exp_f32_e32 v241, v91
	v_exp_f32_e32 v243, v92
	v_exp_f32_e32 v245, v93
	v_exp_f32_e32 v247, v94
	v_exp_f32_e32 v249, v95
	s_waitcnt lgkmcnt(4)
	v_mfma_f32_32x32x16_bf16 v[16:31], v[118:121], v[48:51], v[16:31]
	v_add_f32_e64 v48, v196, v32
	v_add_f32_e64 v49, v197, v33
	v_add_f32_e64 v48, v198, v48
	v_add_f32_e64 v49, v199, v49
	v_add_f32_e64 v48, v200, v48
	v_add_f32_e64 v49, v201, v49
	v_pk_add_f32 v[48:49], v[202:203], v[48:49]
	s_waitcnt lgkmcnt(3)
	v_mfma_f32_32x32x16_bf16 v[32:47], v[118:121], v[52:55], 0
	v_add_f32_e64 v48, v204, v48
	v_add_f32_e64 v49, v205, v49
	v_add_f32_e64 v48, v234, v48
	v_add_f32_e64 v49, v235, v49
	v_add_f32_e64 v48, v236, v48
	v_add_f32_e64 v49, v237, v49
	v_pk_add_f32 v[48:49], v[238:239], v[48:49]
	s_waitcnt lgkmcnt(1)
	v_mfma_f32_32x32x16_bf16 v[32:47], v[118:121], v[60:63], v[32:47]
	v_add_f32_e64 v80, v240, v48
	v_add_f32_e64 v81, v241, v49
	v_add_f32_e64 v80, v242, v80
	v_add_f32_e64 v81, v243, v81
	v_add_f32_e64 v80, v244, v80
	v_add_f32_e64 v81, v245, v81
	v_pk_add_f32 v[80:81], v[246:247], v[80:81]
	v_mfma_f32_32x32x16_bf16 v[48:63], v[118:121], v[56:59], 0
	v_add_f32_e64 v80, v248, v80
	v_add_f32_e64 v81, v249, v81
	v_add_f32_e32 v80, 0, v80
	s_waitcnt lgkmcnt(0)
	v_mfma_f32_32x32x16_bf16 v[48:63], v[118:121], v[114:117], v[48:63]
	s_setprio 0
	v_readlane_b32 s0, v252, 14
	s_mov_b32 m0, s0
	v_readlane_b32 s0, v252, 17
	s_waitcnt vmcnt(4)
	s_barrier
; #define AT_LDK(bufoff, kbi) do { _Pragma("unroll") for (int s_ = 0; s_ < 4; ++s_) kf[s_] = *(const LAS bf16x8*)(kl_ + (bufoff) + ((2 * s_) * 64 + 32 * (kbi)) * 16); } while (0)
; #define AT_LDV(bufoff, kbi) do { _Pragma("unroll") for (int db_ = 0; db_ < 4; ++db_) { vf[2 * db_] = *(const LAS bf16x8*)(vl_ + (bufoff) + ((4 * (kbi)) * 128 + 32 * db_) * 16); vf[2 * db_ + 1] = *(const LAS bf16x8*)(vl_ + (bufoff) + ((4 * (kbi) + 2) * 128 + 32 * db_) * 16); } } while (0)
; #define AT_MQK(dst) do { dst = __builtin_amdgcn_mfma_f32_32x32x16_bf16(kf[0], qf[0], negm, 0, 0, 0); _Pragma("unroll") for (int s_ = 1; s_ < 4; ++s_) dst = __builtin_amdgcn_mfma_f32_32x32x16_bf16(kf[s_], qf[s_], dst, 0, 0, 0); } while (0)
; #define AT_MPV(pk0_, pk1_) do { _Pragma("unroll") for (int db_ = 0; db_ < 4; ++db_) { o[db_] = __builtin_amdgcn_mfma_f32_32x32x16_bf16(pk0_, vf[2 * db_], o[db_], 0, 0, 0); o[db_] = __builtin_amdgcn_mfma_f32_32x32x16_bf16(pk1_, vf[2 * db_ + 1], o[db_], 0, 0, 0); } } while (0)
; #define AT_SM(src, pk0_, pk1_) do { float ls_ = 0.f; _Pragma("unroll") for (int r_ = 0; r_ < 16; ++r_) { src[r_] = __builtin_amdgcn_exp2f(src[r_]); ls_ += src[r_]; } lsum += ls_; pk0_ = pack8(src, 0); pk1_ = pack8(src, 8); } while (0)
; #define AT_SB() __builtin_amdgcn_sched_barrier(0)
; __device__ __forceinline__ void attn_unit(const Params& p, int l, int b, int h, int qpos0, int kbeg, int nkt, int grow0, float lam, float lam_init, unsigned char* lds, int wid0) {
;     ...
;     for (int it = 0; it < nkt; ++it) {
;         AT_LDK(bo, 1); AT_LDV((it ? bop : bo), 1); AT_SB();
;         AT_SM(Sc, pB0, pB1); AT_SB();
;         __builtin_amdgcn_s_setprio(3); AT_MQK(Sn); AT_MPV(pA0, pA1); __builtin_amdgcn_s_setprio(0); AT_SB();
;         if (it + 2 < nkt) asm volatile("s_waitcnt vmcnt(4)" ::: "memory"); else asm volatile("s_waitcnt vmcnt(0)" ::: "memory");
;         __syncthreads();
;         if (it + 3 < nkt) AT_DMA(kt0 + it + 3, (bop >> 15));
;         if (it + 1 < nkt) AT_LDK(bo1, 0);
;         AT_LDV(bo, 0); AT_SB();
;         AT_SM(Sn, pA0, pA1); AT_SB();
;         __builtin_amdgcn_s_setprio(3); if (it + 1 < nkt) AT_MQK(Sc);
;         AT_MPV(pB0, pB1); __builtin_amdgcn_s_setprio(0); AT_SB();
	global_load_lds_dwordx4 v[152:153], off
	s_mov_b32 m0, s0
	v_readlane_b32 s0, v252, 16
	global_load_lds_dwordx4 v[154:155], off
	s_mov_b32 m0, s0
	v_readlane_b32 s0, v252, 15
	global_load_lds_dwordx4 v[148:149], off
	s_mov_b32 m0, s0
	s_nop 0
	global_load_lds_dwordx4 v[150:151], off
	ds_read_b128 v[148:151], v138 offset:32768
	ds_read_b128 v[152:155], v138 offset:34816
	ds_read_b128 v[156:159], v138 offset:36864
	ds_read_b128 v[160:163], v138 offset:38912
	ds_read_b128 v[164:167], v142 offset:16384
	ds_read_b128 v[168:171], v142 offset:16896
	ds_read_b128 v[172:175], v142 offset:20480
	ds_read_b128 v[176:179], v142 offset:20992
	ds_read_b128 v[180:183], v142 offset:17408
	ds_read_b128 v[184:187], v142 offset:17920
	ds_read_b128 v[188:191], v142 offset:21504
	ds_read_b128 v[192:195], v142 offset:22016
	v_add_f32_e32 v139, v80, v81
	v_cvt_pk_bf16_f32 v114, v129, v137
	v_cvt_pk_bf16_f32 v115, v141, v197
	v_cvt_pk_bf16_f32 v116, v199, v201
	v_cvt_pk_bf16_f32 v117, v203, v205
	v_cvt_pk_bf16_f32 v118, v235, v237
	v_cvt_pk_bf16_f32 v119, v239, v241
	v_cvt_pk_bf16_f32 v120, v243, v245
	v_cvt_pk_bf16_f32 v121, v247, v249
	s_setprio 3
	s_waitcnt lgkmcnt(0)
	v_mfma_f32_32x32x16_bf16 v[80:95], v[148:151], v[110:113], v[64:79]
	v_mfma_f32_32x32x16_bf16 v[80:95], v[152:155], v[102:105], v[80:95]
	v_mfma_f32_32x32x16_bf16 v[80:95], v[156:159], v[106:109], v[80:95]
	v_mfma_f32_32x32x16_bf16 v[0:15], v[124:127], v[164:167], v[0:15]
	v_mfma_f32_32x32x16_bf16 v[16:31], v[124:127], v[168:171], v[16:31]
	v_mfma_f32_32x32x16_bf16 v[32:47], v[124:127], v[180:183], v[32:47]
	v_mfma_f32_32x32x16_bf16 v[48:63], v[124:127], v[184:187], v[48:63]
	v_mfma_f32_32x32x16_bf16 v[80:95], v[160:163], v[98:101], v[80:95]
	v_mfma_f32_32x32x16_bf16 v[0:15], v[144:147], v[172:175], v[0:15]
	v_mfma_f32_32x32x16_bf16 v[16:31], v[144:147], v[176:179], v[16:31]
	v_mfma_f32_32x32x16_bf16 v[32:47], v[144:147], v[188:191], v[32:47]
	v_mfma_f32_32x32x16_bf16 v[48:63], v[144:147], v[192:195], v[48:63]
	s_setprio 0
	s_add_u32 s0, s34, s54
	s_addc_u32 s1, s35, 0
	v_lshl_add_u64 v[136:137], s[0:1], 0, v[122:123]
	s_lshl_b32 s0, s64, 14
	s_add_i32 s75, s0, 0xffff4000
	s_mov_b32 s54, 0x18000
	s_mov_b64 s[0:1], 0
	v_add_u32_e32 v234, s82, v142
	ds_read_b128 v[174:177], v234 offset:24576
	ds_read_b128 v[178:181], v234 offset:25088
	ds_read_b128 v[182:185], v234 offset:25600
	ds_read_b128 v[186:189], v234 offset:26112
	ds_read_b128 v[190:193], v234 offset:28672
	ds_read_b128 v[194:197], v234 offset:29184
	ds_read_b128 v[198:201], v234 offset:29696
	ds_read_b128 v[202:205], v234 offset:30208
	v_add_u32_e32 v235, s65, v138
	ds_read_b128 v[158:161], v235 offset:512
	ds_read_b128 v[162:165], v235 offset:2560
	ds_read_b128 v[166:169], v235 offset:4608
	ds_read_b128 v[170:173], v235 offset:6656
	.p2alignl 6, 3212836864

; __device__ __forceinline__ void hyena_channel(const Params& p, int l, int c, unsigned char* lds, int wid0) {
;     ...
;         __syncthreads();
;         fft_pass16<false, 10>(X, tid); __syncthreads();
;         fft_pass16<false, 6>(X, tid); __syncthreads();
;         fft_pass16<false, 2>(X, tid); __syncthreads();
.LBB0_278:
	s_xor_b64 s[0:1], s[38:39], -1
	s_mov_b32 s24, 0
	s_mov_b64 s[38:39], -1
	s_waitcnt lgkmcnt(0)
	s_barrier
	.p2alignl 6, 3212836864

; template <bool INV, int LQ> __device__ __forceinline__ void fft_pass16(f32x2* X, int tid) {
;     constexpr int q = 1 << LQ, STR = q + 4 * (q >> 6);
; #pragma unroll 1
;     for (int gg = 0; gg < 2; ++gg) {
;         const int g = tid + 512 * gg, blk = g >> LQ, i = g & (q - 1), base = (blk << (LQ + 4)) + i;
;         f32x2* xb = X + fidx(base);
;         cf a[16];
; #pragma unroll
;         for (int j = 0; j < 16; ++j) { const f32x2 v = xb[j * STR]; a[j] = {v.x, v.y}; }
;         const float rev = (float)i * (1.f / (float)(16 << LQ));
;         const cf w1 = {__builtin_amdgcn_cosf(rev), __builtin_amdgcn_sinf(rev)};
;         if (!INV) {
;             dft16<false>(a);
;             cf w = w1;
; #pragma unroll
;             for (int k = 1; k < 16; ++k) { const int src = 4 * (k & 3) + (k >> 2);
;                 const cf y = cmulc(a[src], w); xb[k * STR] = (f32x2){y.x, y.y}; w = cmul(w, w1); }
;             xb[0] = (f32x2){a[0].x, a[0].y};
;         } else {
;             cf w = w1;
; #pragma unroll
;             for (int k = 1; k < 16; ++k) { a[k] = cmul(a[k], w); w = cmul(w, w1); }
.LBB0_294:
	v_add_u32_e32 v0, s24, v242
	v_and_b32_e32 v0, 0xfffffc00, v0
	v_ashrrev_i32_e32 v1, 1, v0
	v_add_u32_e32 v1, 0, v1
	v_lshlrev_b32_e32 v0, 3, v0
	v_add3_u32 v127, v1, v0, v96
	ds_read2_b64 v[14:17], v127 offset1:68
	ds_read2_b64 v[0:3], v127 offset0:136 offset1:204
	v_add_u32_e32 v128, 0x800, v127
	ds_read2_b64 v[4:7], v128 offset0:16 offset1:84
	ds_read2_b64 v[8:11], v128 offset0:152 offset1:220
	v_add_u32_e32 v129, 0x1000, v127
	s_waitcnt lgkmcnt(3)
	v_pk_mul_f32 v[12:13], v[44:45], v[16:17]
	ds_read2_b64 v[18:21], v129 offset0:32 offset1:100
	ds_read2_b64 v[22:25], v129 offset0:168 offset1:236
	v_pk_fma_f32 v[108:109], v[42:43], v[16:17], v[12:13] op_sel:[0,0,1] op_sel_hi:[1,1,0] neg_lo:[0,0,1] neg_hi:[0,0,1]
	v_pk_fma_f32 v[12:13], v[42:43], v[16:17], v[12:13] op_sel:[0,0,1] op_sel_hi:[1,1,0]
	s_waitcnt lgkmcnt(4)
	v_pk_mul_f32 v[16:17], v[48:49], v[0:1]
	v_add_u32_e32 v126, 0x1800, v127
	v_pk_fma_f32 v[112:113], v[46:47], v[0:1], v[16:17] op_sel:[0,0,1] op_sel_hi:[1,1,0] neg_lo:[0,0,1] neg_hi:[0,0,1]
	v_pk_fma_f32 v[0:1], v[46:47], v[0:1], v[16:17] op_sel:[0,0,1] op_sel_hi:[1,1,0]
	v_pk_mul_f32 v[16:17], v[52:53], v[2:3]
	ds_read2_b64 v[26:29], v126 offset0:48 offset1:116
	ds_read2_b64 v[30:33], v126 offset0:184 offset1:252
	v_pk_fma_f32 v[116:117], v[50:51], v[2:3], v[16:17] op_sel:[0,0,1] op_sel_hi:[1,1,0] neg_lo:[0,0,1] neg_hi:[0,0,1]
	v_pk_fma_f32 v[2:3], v[50:51], v[2:3], v[16:17] op_sel:[0,0,1] op_sel_hi:[1,1,0]
	s_waitcnt lgkmcnt(5)
	v_pk_mul_f32 v[16:17], v[56:57], v[4:5]
	v_mov_b32_e32 v109, v13
	v_pk_fma_f32 v[122:123], v[54:55], v[4:5], v[16:17] op_sel:[0,0,1] op_sel_hi:[1,1,0] neg_lo:[0,0,1] neg_hi:[0,0,1]
	v_pk_fma_f32 v[4:5], v[54:55], v[4:5], v[16:17] op_sel:[0,0,1] op_sel_hi:[1,1,0]
	v_mov_b32_e32 v113, v1
	v_mov_b32_e32 v123, v5
	v_pk_mul_f32 v[4:5], v[60:61], v[6:7]
	v_mov_b32_e32 v117, v3
	v_pk_fma_f32 v[16:17], v[58:59], v[6:7], v[4:5] op_sel:[0,0,1] op_sel_hi:[1,1,0] neg_lo:[0,0,1] neg_hi:[0,0,1]
	v_pk_fma_f32 v[4:5], v[58:59], v[6:7], v[4:5] op_sel:[0,0,1] op_sel_hi:[1,1,0]
	s_waitcnt lgkmcnt(4)
	v_pk_mul_f32 v[6:7], v[64:65], v[8:9]
	v_pk_mov_b32 v[12:13], v[12:13], v[16:17] op_sel:[1,0]
	v_pk_fma_f32 v[114:115], v[62:63], v[8:9], v[6:7] op_sel:[0,0,1] op_sel_hi:[1,1,0] neg_lo:[0,0,1] neg_hi:[0,0,1]
	v_pk_fma_f32 v[6:7], v[62:63], v[8:9], v[6:7] op_sel:[0,0,1] op_sel_hi:[1,1,0]
	v_pk_mul_f32 v[8:9], v[68:69], v[10:11]
	v_mov_b32_e32 v4, v16
	v_pk_fma_f32 v[118:119], v[66:67], v[10:11], v[8:9] op_sel:[0,0,1] op_sel_hi:[1,1,0] neg_lo:[0,0,1] neg_hi:[0,0,1]
	v_pk_fma_f32 v[8:9], v[66:67], v[10:11], v[8:9] op_sel:[0,0,1] op_sel_hi:[1,1,0]
	s_waitcnt lgkmcnt(3)
	v_pk_mul_f32 v[10:11], v[72:73], v[18:19]
	v_mov_b32_e32 v6, v114
	v_pk_fma_f32 v[124:125], v[70:71], v[18:19], v[10:11] op_sel:[0,0,1] op_sel_hi:[1,1,0] neg_lo:[0,0,1] neg_hi:[0,0,1]
	v_pk_fma_f32 v[10:11], v[70:71], v[18:19], v[10:11] op_sel:[0,0,1] op_sel_hi:[1,1,0]
	v_mov_b32_e32 v8, v118
	v_mov_b32_e32 v125, v11
	v_pk_mul_f32 v[10:11], v[76:77], v[20:21]
	v_pk_mov_b32 v[0:1], v[0:1], v[114:115] op_sel:[1,0]
	v_pk_fma_f32 v[18:19], v[74:75], v[20:21], v[10:11] op_sel:[0,0,1] op_sel_hi:[1,1,0] neg_lo:[0,0,1] neg_hi:[0,0,1]
	v_pk_fma_f32 v[10:11], v[74:75], v[20:21], v[10:11] op_sel:[0,0,1] op_sel_hi:[1,1,0]
	s_waitcnt lgkmcnt(2)
	v_pk_mul_f32 v[20:21], v[80:81], v[22:23]
	v_mov_b32_e32 v19, v11
	v_pk_fma_f32 v[120:121], v[78:79], v[22:23], v[20:21] op_sel:[0,0,1] op_sel_hi:[1,1,0] neg_lo:[0,0,1] neg_hi:[0,0,1]
	v_pk_fma_f32 v[20:21], v[78:79], v[22:23], v[20:21] op_sel:[0,0,1] op_sel_hi:[1,1,0]
	v_pk_mul_f32 v[22:23], v[84:85], v[24:25]
	v_mov_b32_e32 v121, v21
	v_pk_fma_f32 v[132:133], v[82:83], v[24:25], v[22:23] op_sel:[0,0,1] op_sel_hi:[1,1,0] neg_lo:[0,0,1] neg_hi:[0,0,1]
	v_pk_fma_f32 v[134:135], v[82:83], v[24:25], v[22:23] op_sel:[0,0,1] op_sel_hi:[1,1,0]
	s_waitcnt lgkmcnt(1)
	v_pk_mul_f32 v[22:23], v[88:89], v[26:27]
	v_mov_b32_e32 v133, v135
	v_pk_fma_f32 v[136:137], v[86:87], v[26:27], v[22:23] op_sel:[0,0,1] op_sel_hi:[1,1,0] neg_lo:[0,0,1] neg_hi:[0,0,1]
	v_pk_fma_f32 v[22:23], v[86:87], v[26:27], v[22:23] op_sel:[0,0,1] op_sel_hi:[1,1,0]
	v_pk_add_f32 v[98:99], v[14:15], v[124:125]
	v_mov_b32_e32 v137, v23
	v_pk_mul_f32 v[22:23], v[92:93], v[28:29]
	v_pk_add_f32 v[106:107], v[122:123], v[136:137]
	v_pk_fma_f32 v[24:25], v[90:91], v[28:29], v[22:23] op_sel:[0,0,1] op_sel_hi:[1,1,0] neg_lo:[0,0,1] neg_hi:[0,0,1]
	v_pk_fma_f32 v[26:27], v[90:91], v[28:29], v[22:23] op_sel:[0,0,1] op_sel_hi:[1,1,0]
	s_waitcnt lgkmcnt(0)
; template <bool INV> __device__ __forceinline__ void dft4(cf& a0, cf& a1, cf& a2, cf& a3) {
;     const cf t0 = cadd(a0, a2), t1 = csub(a0, a2), t2 = cadd(a1, a3), t3 = csub(a1, a3);
;     a0 = cadd(t0, t2); a2 = csub(t0, t2);
;     if (!INV) { a1 = {t1.x + t3.y, t1.y - t3.x}; a3 = {t1.x - t3.y, t1.y + t3.x}; }
;     else      { a1 = {t1.x - t3.y, t1.y + t3.x}; a3 = {t1.x + t3.y, t1.y - t3.x}; }
; }
; template <bool INV> __device__ __forceinline__ void dft16(cf (&a)[16]) {
; #pragma unroll
;     for (int n2 = 0; n2 < 4; ++n2) dft4<INV>(a[n2], a[4 + n2], a[8 + n2], a[12 + n2]);
; #pragma unroll
;     for (int k1 = 1; k1 < 4; ++k1)
; #pragma unroll
;         for (int n2 = 1; n2 < 4; ++n2) { const cf w = {W16C(n2 * k1), W16S(n2 * k1)};
;             a[4 * k1 + n2] = INV ? cmul(a[4 * k1 + n2], w) : cmulc(a[4 * k1 + n2], w); }
; #pragma unroll
;     for (int k1 = 0; k1 < 4; ++k1) dft4<INV>(a[4 * k1 + 0], a[4 * k1 + 1], a[4 * k1 + 2], a[4 * k1 + 3]);
	v_pk_mul_f32 v[22:23], v[100:101], v[30:31]
	v_pk_mov_b32 v[10:11], v[10:11], v[24:25] op_sel:[1,0]
	v_pk_fma_f32 v[28:29], v[94:95], v[30:31], v[22:23] op_sel:[0,0,1] op_sel_hi:[1,1,0] neg_lo:[0,0,1] neg_hi:[0,0,1]
	v_pk_fma_f32 v[130:131], v[94:95], v[30:31], v[22:23] op_sel:[0,0,1] op_sel_hi:[1,1,0]
	v_pk_mul_f32 v[22:23], v[104:105], v[32:33]
	v_pk_add_f32 v[30:31], v[108:109], v[18:19]
	v_pk_fma_f32 v[138:139], v[102:103], v[32:33], v[22:23] op_sel:[0,0,1] op_sel_hi:[1,1,0] neg_lo:[0,0,1] neg_hi:[0,0,1]
	v_pk_fma_f32 v[140:141], v[102:103], v[32:33], v[22:23] op_sel:[0,0,1] op_sel_hi:[1,1,0]
	v_mov_b32_e32 v109, v5
	v_mov_b32_e32 v19, v27
	v_mov_b32_e32 v26, v24
	v_mov_b32_e32 v130, v28
	v_mov_b32_e32 v140, v138
	v_pk_add_f32 v[22:23], v[12:13], v[10:11] neg_lo:[0,1] neg_hi:[0,1]
	v_pk_add_f32 v[24:25], v[108:109], v[18:19] neg_lo:[0,1] neg_hi:[0,1]
	v_pk_add_f32 v[108:109], v[112:113], v[120:121]
	v_pk_mov_b32 v[10:11], v[20:21], v[28:29] op_sel:[1,0]
	v_mov_b32_e32 v113, v7
	v_mov_b32_e32 v121, v131
	v_pk_add_f32 v[32:33], v[4:5], v[26:27]
	v_pk_add_f32 v[110:111], v[6:7], v[130:131]
	v_pk_add_f32 v[26:27], v[0:1], v[10:11] neg_lo:[0,1] neg_hi:[0,1]
	v_pk_add_f32 v[28:29], v[112:113], v[120:121] neg_lo:[0,1] neg_hi:[0,1]
	v_pk_add_f32 v[112:113], v[116:117], v[132:133]
	v_pk_add_f32 v[114:115], v[8:9], v[140:141]
	v_pk_mov_b32 v[0:1], v[2:3], v[118:119] op_sel:[1,0]
	v_pk_mov_b32 v[2:3], v[134:135], v[138:139] op_sel:[1,0]
	v_mov_b32_e32 v117, v9
	v_mov_b32_e32 v133, v141
	v_pk_add_f32 v[142:143], v[98:99], v[106:107]
	v_pk_add_f32 v[10:11], v[108:109], v[110:111]
	v_add_f32_e32 v6, v26, v27
	v_pk_add_f32 v[118:119], v[0:1], v[2:3] neg_lo:[0,1] neg_hi:[0,1]
	v_pk_add_f32 v[120:121], v[116:117], v[132:133] neg_lo:[0,1] neg_hi:[0,1]
	v_pk_add_f32 v[2:3], v[112:113], v[114:115]
	v_pk_add_f32 v[98:99], v[98:99], v[106:107] neg_lo:[0,1] neg_hi:[0,1]
	v_pk_add_f32 v[106:107], v[108:109], v[110:111] neg_lo:[0,1] neg_hi:[0,1]
	v_mov_b32_e32 v109, v112
	v_mov_b32_e32 v111, v114
	v_mov_b32_e32 v112, v31
	v_mov_b32_e32 v114, v33
	v_pk_add_f32 v[4:5], v[30:31], v[32:33]
	v_mul_f32_e32 v117, 0x3f3504f3, v6
	v_mov_b32_e32 v0, v118
	v_mov_b32_e32 v1, v120
	v_mov_b32_e32 v6, v119
	v_mov_b32_e32 v7, v121
	v_mov_b32_e32 v108, v30
	v_mov_b32_e32 v110, v32
	v_pk_add_f32 v[30:31], v[112:113], v[114:115] neg_lo:[0,1] neg_hi:[0,1]
	v_pk_add_f32 v[12:13], v[0:1], v[6:7] neg_lo:[0,1] neg_hi:[0,1]
	v_pk_add_f32 v[20:21], v[0:1], v[6:7]
	v_pk_add_f32 v[108:109], v[108:109], v[110:111] neg_lo:[0,1] neg_hi:[0,1]
	v_pk_mul_f32 v[30:31], v[30:31], s[70:71] op_sel_hi:[1,0]
	v_mov_b32_e32 v13, v21
	v_mul_f32_e32 v0, 0x3ec3ef15, v21
	v_pk_fma_f32 v[32:33], v[106:107], 0, v[106:107] op_sel:[0,0,1] op_sel_hi:[1,0,0] neg_lo:[0,0,1] neg_hi:[0,0,1]
	v_pk_fma_f32 v[106:107], v[106:107], 0, v[106:107] op_sel:[0,0,1] op_sel_hi:[1,0,0]
	v_pk_fma_f32 v[110:111], v[108:109], s[70:71], v[30:31] neg_lo:[0,0,1] neg_hi:[0,0,1]
	v_pk_fma_f32 v[112:113], v[108:109], s[70:71], v[30:31]
	v_pk_fma_f32 v[108:109], v[108:109], s[70:71], v[30:31] op_sel_hi:[1,0,1] neg_lo:[0,0,1] neg_hi:[0,0,1]
	v_pk_fma_f32 v[8:9], v[12:13], s[2:3], v[0:1] op_sel_hi:[1,1,0] neg_lo:[0,0,1] neg_hi:[0,0,1]
	v_pk_add_f32 v[0:1], v[142:143], v[10:11]
	v_pk_add_f32 v[16:17], v[4:5], v[2:3]
	v_mov_b32_e32 v33, v107
	v_pk_mov_b32 v[106:107], v[110:111], v[112:113] op_sel:[1,0]
	v_mov_b32_e32 v113, v108
	v_mov_b32_e32 v110, v109
	v_sub_f32_e32 v130, v28, v29
	v_pk_add_f32 v[6:7], v[0:1], v[16:17]
	v_pk_add_f32 v[0:1], v[0:1], v[16:17] neg_lo:[0,1] neg_hi:[0,1]
	v_pk_add_f32 v[16:17], v[14:15], v[124:125] neg_lo:[0,1] neg_hi:[0,1]
	v_pk_add_f32 v[124:125], v[24:25], v[24:25] op_sel:[0,1] op_sel_hi:[0,1] neg_lo:[0,1] neg_hi:[0,1]
	v_pk_add_f32 v[132:133], v[22:23], v[22:23] op_sel:[0,1] op_sel_hi:[0,1]
	v_pk_add_f32 v[114:115], v[108:109], v[106:107]
	v_pk_add_f32 v[108:109], v[112:113], v[110:111] neg_lo:[0,1] neg_hi:[0,1]
	v_mov_b32_e32 v110, v28
	v_mov_b32_e32 v111, v24
	v_mov_b32_e32 v24, v29
	v_mov_b32_e32 v28, v26
	v_mov_b32_e32 v29, v22
	v_mov_b32_e32 v22, v27
	v_pk_add_f32 v[14:15], v[122:123], v[136:137] neg_lo:[0,1] neg_hi:[0,1]
	s_mov_b32 s38, s67
	s_mov_b32 s39, s66
	v_pk_mul_f32 v[132:133], v[132:133], s[66:67]
	v_pk_add_f32 v[118:119], v[118:119], v[118:119] op_sel:[0,1] op_sel_hi:[0,1]
	v_pk_add_f32 v[22:23], v[28:29], v[22:23] neg_lo:[0,1] neg_hi:[0,1]
; template <bool INV> __device__ __forceinline__ void dft16(cf (&a)[16]) {
;     ...
;             a[4 * k1 + n2] = INV ? cmul(a[4 * k1 + n2], w) : cmulc(a[4 * k1 + n2], w); }
; #pragma unroll
;     for (int k1 = 0; k1 < 4; ++k1) dft4<INV>(a[4 * k1 + 0], a[4 * k1 + 1], a[4 * k1 + 2], a[4 * k1 + 3]);
; }
; template <bool INV, int LQ> __device__ __forceinline__ void fft_pass16(f32x2* X, int tid) {
;     constexpr int q = 1 << LQ, STR = q + 4 * (q >> 6);
; #pragma unroll 1
;     for (int gg = 0; gg < 2; ++gg) {
;         const int g = tid + 512 * gg, blk = g >> LQ, i = g & (q - 1), base = (blk << (LQ + 4)) + i;
;         f32x2* xb = X + fidx(base);
;         cf a[16];
; #pragma unroll
;         for (int j = 0; j < 16; ++j) { const f32x2 v = xb[j * STR]; a[j] = {v.x, v.y}; }
;         const float rev = (float)i * (1.f / (float)(16 << LQ));
;         const cf w1 = {__builtin_amdgcn_cosf(rev), __builtin_amdgcn_sinf(rev)};
;         if (!INV) {
;             dft16<false>(a);
;             cf w = w1;
; #pragma unroll
;             for (int k = 1; k < 16; ++k) { const int src = 4 * (k & 3) + (k >> 2);
;                 const cf y = cmulc(a[src], w); xb[k * STR] = (f32x2){y.x, y.y}; w = cmul(w, w1); }
;             xb[0] = (f32x2){a[0].x, a[0].y};
;         } else {
;             cf w = w1;
; #pragma unroll
;             for (int k = 1; k < 16; ++k) { a[k] = cmul(a[k], w); w = cmul(w, w1); }
;             dft16<true>(a);
; #pragma unroll
;             for (int k = 0; k < 16; ++k) { const int src = 4 * (k & 3) + (k >> 2); xb[k * STR] = (f32x2){a[src].x, a[src].y}; }
;         }
; __device__ __forceinline__ void hyena_channel(const Params& p, int l, int c, unsigned char* lds, int wid0) {
;     ...
;     fft_pass16<true, 2>(X, tid); __syncthreads();
;     fft_pass16<true, 6>(X, tid); __syncthreads();
;     fft_pass16<true, 10>(X, tid); __syncthreads();
	s_mov_b32 s40, s70
	s_mov_b32 s41, s66
	v_mul_f32_e32 v116, 0x3f3504f3, v130
	v_pk_mov_b32 v[18:19], v[14:15], v[14:15] op_sel:[1,0]
	v_pk_fma_f32 v[134:135], v[124:125], s[38:39], v[132:133] neg_lo:[0,0,1] neg_hi:[0,0,1]
	v_pk_fma_f32 v[124:125], v[124:125], s[38:39], v[132:133]
	v_pk_add_f32 v[120:121], v[120:121], v[120:121] op_sel:[0,1] op_sel_hi:[0,1] neg_lo:[0,1] neg_hi:[0,1]
	v_pk_mul_f32 v[118:119], v[118:119], s[38:39]
	v_pk_add_f32 v[24:25], v[110:111], v[24:25]
	s_mov_b32 s38, s71
	s_mov_b32 s39, s67
	v_pk_mul_f32 v[26:27], v[22:23], s[40:41]
	v_pk_mov_b32 v[20:21], v[20:21], v[22:23] op_sel:[1,0]
	s_mov_b32 s40, s25
	s_mov_b32 s41, s71
	v_pk_add_f32 v[122:123], v[16:17], v[14:15] op_sel:[0,1] op_sel_hi:[1,0] neg_lo:[0,1] neg_hi:[0,1]
	v_pk_add_f32 v[14:15], v[16:17], v[14:15] op_sel:[0,1] op_sel_hi:[1,0]
	v_sub_f32_e32 v116, v116, v117
	v_fmac_f32_e32 v117, 0x3f3504f3, v130
	v_pk_fma_f32 v[130:131], v[120:121], s[66:67], v[118:119] neg_lo:[0,0,1] neg_hi:[0,0,1]
	v_pk_fma_f32 v[118:119], v[120:121], s[66:67], v[118:119]
	v_mul_f32_e32 v16, 0x3ec3ef15, v25
	v_mul_f32_e32 v18, 0x3f6c835e, v23
	v_pk_mul_f32 v[20:21], v[20:21], s[40:41]
	v_pk_fma_f32 v[22:23], v[24:25], s[38:39], v[26:27] neg_lo:[0,0,1] neg_hi:[0,0,1]
	v_pk_fma_f32 v[26:27], v[24:25], s[38:39], v[26:27]
	v_mov_b32_e32 v13, v24
	v_mov_b32_e32 v123, v15
	v_mov_b32_e32 v135, v125
	v_mov_b32_e32 v131, v119
	v_mov_b32_e32 v23, v27
	v_pk_fma_f32 v[12:13], v[12:13], s[96:97], v[20:21]
	v_pk_add_f32 v[16:17], v[16:17], v[18:19] neg_lo:[0,1] neg_hi:[0,1]
	v_mov_b32_e32 v15, v8
	v_pk_add_f32 v[118:119], v[122:123], v[116:117]
	v_pk_add_f32 v[120:121], v[134:135], v[130:131]
	v_pk_add_f32 v[18:19], v[16:17], v[12:13]
	v_pk_add_f32 v[20:21], v[22:23], v[14:15]
	v_mov_b32_e32 v15, v17
	v_mov_b32_e32 v23, v13
	v_pk_mov_b32 v[16:17], v[26:27], v[16:17] op_sel:[1,0]
	v_mov_b32_e32 v9, v12
	v_pk_add_f32 v[10:11], v[142:143], v[10:11] neg_lo:[0,1] neg_hi:[0,1]
	v_pk_add_f32 v[2:3], v[4:5], v[2:3] neg_lo:[0,1] neg_hi:[0,1]
	v_pk_add_f32 v[124:125], v[118:119], v[120:121]
	v_pk_add_f32 v[118:119], v[118:119], v[120:121] neg_lo:[0,1] neg_hi:[0,1]
	v_pk_add_f32 v[120:121], v[122:123], v[116:117] neg_lo:[0,1] neg_hi:[0,1]
	v_pk_add_f32 v[122:123], v[134:135], v[130:131] neg_lo:[0,1] neg_hi:[0,1]
	v_pk_add_f32 v[30:31], v[98:99], v[32:33]
	v_pk_add_f32 v[32:33], v[98:99], v[32:33] neg_lo:[0,1] neg_hi:[0,1]
	v_pk_add_f32 v[14:15], v[14:15], v[22:23] neg_lo:[0,1] neg_hi:[0,1]
	v_pk_add_f32 v[8:9], v[16:17], v[8:9] neg_lo:[0,1] neg_hi:[0,1]
	v_pk_add_f32 v[4:5], v[10:11], v[2:3] op_sel:[0,1] op_sel_hi:[1,0] neg_lo:[0,1] neg_hi:[0,1]
	v_pk_add_f32 v[2:3], v[10:11], v[2:3] op_sel:[0,1] op_sel_hi:[1,0]
	v_pk_add_f32 v[116:117], v[120:121], v[122:123] op_sel:[0,1] op_sel_hi:[1,0] neg_lo:[0,1] neg_hi:[0,1]
	v_pk_add_f32 v[120:121], v[120:121], v[122:123] op_sel:[0,1] op_sel_hi:[1,0]
	v_pk_add_f32 v[98:99], v[32:33], v[108:109] neg_lo:[0,1] neg_hi:[0,1]
	v_pk_add_f32 v[32:33], v[32:33], v[108:109]
	v_pk_add_f32 v[12:13], v[14:15], v[8:9] neg_lo:[0,1] neg_hi:[0,1]
	v_pk_add_f32 v[8:9], v[14:15], v[8:9]
	v_mov_b32_e32 v11, v3
	v_mov_b32_e32 v123, v121
	v_mov_b32_e32 v109, v33
	v_pk_add_f32 v[24:25], v[18:19], v[20:21]
	v_mov_b32_e32 v28, v20
	v_mov_b32_e32 v29, v19
	v_mov_b32_e32 v19, v21
	v_mov_b32_e32 v15, v9
	v_mov_b32_e32 v3, v5
	v_mov_b32_e32 v121, v117
	v_mov_b32_e32 v33, v99
	v_mov_b32_e32 v9, v13
	s_movk_i32 s24, 0x2000
	s_and_b64 vcc, exec, s[0:1]
	s_mov_b64 s[0:1], 0
	v_mov_b32_e32 v10, v4
	v_mov_b32_e32 v122, v116
	v_pk_add_f32 v[106:107], v[30:31], v[114:115]
	v_pk_add_f32 v[30:31], v[30:31], v[114:115] neg_lo:[0,1] neg_hi:[0,1]
	v_mov_b32_e32 v108, v98
	v_pk_add_f32 v[18:19], v[28:29], v[18:19] neg_lo:[0,1] neg_hi:[0,1]
	v_mov_b32_e32 v14, v12
	ds_write2_b64 v127, v[6:7], v[124:125] offset1:68
	ds_write2_b64 v127, v[106:107], v[24:25] offset0:136 offset1:204
	ds_write2_b64 v128, v[10:11], v[122:123] offset0:16 offset1:84
	ds_write2_b64 v128, v[108:109], v[14:15] offset0:152 offset1:220
	ds_write2_b64 v129, v[0:1], v[118:119] offset0:32 offset1:100
	ds_write2_b64 v129, v[30:31], v[18:19] offset0:168 offset1:236
	ds_write2_b64 v126, v[2:3], v[120:121] offset0:48 offset1:116
	ds_write2_b64 v126, v[32:33], v[8:9] offset0:184 offset1:252
	s_cbranch_vccnz .LBB0_294
	s_mov_b32 s24, 0
	s_mov_b64 s[0:1], -1
	s_waitcnt lgkmcnt(0)
	s_barrier
	.p2alignl 6, 3212836864

; template <class Epi, class Sched, bool ALIGN_EPI = false, bool SP2 = false, class Hook = NoHook>
; __device__ __forceinline__ void gemm_phase(PG8_LAS unsigned char* lds, const Gemm g, const Sched& S, const Epi& E, int tid, const Hook& H = Hook()) {
;     ...
;         const bool has_next = S.next(ui + 1, nxt);
;         const char* nA = has_next ? (const char*)g.A + (size_t)nxt.pm * tstep : cA; const char* nB = has_next ? (const char*)g.Bt + (size_t)nxt.pn * tstep : cB;
;         for (int t = 0; t < nt; t += 2) {
;             if constexpr (Hook::ON) { if (t == 8 || t == 16) H(acc, cur, wr, wc, fr, fq, t); }
;             const bool last = (t == nt - 2);
;             const char* a1 = cA + (size_t)(t + 1) * kstep;
;             const char* a2 = last ? nA : cA + (size_t)(t + 2) * kstep; const char* b2 = last ? nB : cB + (size_t)(t + 2) * kstep;
;     ...
;         for (int a = 0; a < 2; ++a)
; #pragma unroll
;             for (int b = 0; b < 2; ++b)
; #pragma unroll
;                 for (int m = 0; m < 4; ++m)
; #pragma unroll
;                     for (int n = 0; n < 2; ++n) acc[a][b][m][n] = (f32x4){0.f, 0.f, 0.f, 0.f};
;         cur = nxt; cA = nA; cB = nB; ++ui;
.LBB0_342:
	s_ashr_i32 s83, s82, 31
	s_lshl_b64 s[46:47], s[82:83], 19
	v_readlane_b32 s4, v253, 7
	v_readlane_b32 s5, v253, 8
	s_add_u32 s94, s4, s46
	s_addc_u32 s95, s5, s47
	s_and_b64 s[46:47], s[40:41], exec
	s_cselect_b32 s35, s95, s1
	s_cselect_b32 s45, s94, s0
	s_ashr_i32 s55, s54, 31
	s_lshl_b64 s[46:47], s[54:55], 19
	v_readlane_b32 s4, v251, 46
	v_readlane_b32 s5, v251, 47
	s_add_u32 s48, s4, s46
	s_addc_u32 s49, s5, s47
	s_and_b64 s[46:47], s[40:41], exec
	s_cselect_b32 s55, s49, s43
	s_cselect_b32 s72, s48, s42
	s_add_u32 s0, s0, 0x40080
	s_addc_u32 s1, s1, 0
	s_add_u32 s73, s42, 0x100
	v_mov_b32_e32 v0, 0
	s_addc_u32 s74, s43, 0
	s_mov_b32 s75, -2
	v_mov_b32_e32 v1, v0
	v_mov_b32_e32 v2, v0
	v_mov_b32_e32 v3, v0
	v_mov_b32_e32 v4, v0
	v_mov_b32_e32 v5, v0
	v_mov_b32_e32 v6, v0
	v_mov_b32_e32 v7, v0
	v_mov_b32_e32 v16, v0
	v_mov_b32_e32 v17, v0
	v_mov_b32_e32 v18, v0
	v_mov_b32_e32 v19, v0
	v_mov_b32_e32 v20, v0
	v_mov_b32_e32 v21, v0
	v_mov_b32_e32 v22, v0
	v_mov_b32_e32 v23, v0
	v_mov_b32_e32 v32, v0
	v_mov_b32_e32 v33, v0
	v_mov_b32_e32 v34, v0
	v_mov_b32_e32 v35, v0
	v_mov_b32_e32 v36, v0
	v_mov_b32_e32 v37, v0
	v_mov_b32_e32 v38, v0
	v_mov_b32_e32 v39, v0
	v_mov_b32_e32 v48, v0
	v_mov_b32_e32 v49, v0
	v_mov_b32_e32 v50, v0
	v_mov_b32_e32 v51, v0
	v_mov_b32_e32 v52, v0
	v_mov_b32_e32 v53, v0
	v_mov_b32_e32 v54, v0
	v_mov_b32_e32 v55, v0
	v_mov_b32_e32 v8, v0
	v_mov_b32_e32 v9, v0
	v_mov_b32_e32 v10, v0
	v_mov_b32_e32 v11, v0
	v_mov_b32_e32 v12, v0
	v_mov_b32_e32 v13, v0
	v_mov_b32_e32 v14, v0
	v_mov_b32_e32 v15, v0
	v_mov_b32_e32 v24, v0
	v_mov_b32_e32 v25, v0
	v_mov_b32_e32 v26, v0
	v_mov_b32_e32 v27, v0
	v_mov_b32_e32 v28, v0
	v_mov_b32_e32 v29, v0
	v_mov_b32_e32 v30, v0
	v_mov_b32_e32 v31, v0
	v_mov_b32_e32 v40, v0
	v_mov_b32_e32 v41, v0
	v_mov_b32_e32 v42, v0
	v_mov_b32_e32 v43, v0
	v_mov_b32_e32 v44, v0
	v_mov_b32_e32 v45, v0
	v_mov_b32_e32 v46, v0
	v_mov_b32_e32 v47, v0
	v_mov_b32_e32 v56, v0
	v_mov_b32_e32 v57, v0
	v_mov_b32_e32 v58, v0
	v_mov_b32_e32 v59, v0
	v_mov_b32_e32 v60, v0
	v_mov_b32_e32 v61, v0
	v_mov_b32_e32 v62, v0
	v_mov_b32_e32 v63, v0
	v_mov_b32_e32 v64, v0
	v_mov_b32_e32 v65, v0
	v_mov_b32_e32 v66, v0
	v_mov_b32_e32 v67, v0
	v_mov_b32_e32 v68, v0
	v_mov_b32_e32 v69, v0
	v_mov_b32_e32 v70, v0
	v_mov_b32_e32 v71, v0
	v_mov_b32_e32 v80, v0
	v_mov_b32_e32 v81, v0
	v_mov_b32_e32 v82, v0
	v_mov_b32_e32 v83, v0
	v_mov_b32_e32 v84, v0
	v_mov_b32_e32 v85, v0
	v_mov_b32_e32 v86, v0
	v_mov_b32_e32 v87, v0
	v_mov_b32_e32 v98, v0
	v_mov_b32_e32 v99, v0
	v_mov_b32_e32 v100, v0
	v_mov_b32_e32 v101, v0
	v_mov_b32_e32 v102, v0
	v_mov_b32_e32 v103, v0
	v_mov_b32_e32 v104, v0
	v_mov_b32_e32 v105, v0
	v_mov_b32_e32 v114, v0
	v_mov_b32_e32 v115, v0
	v_mov_b32_e32 v116, v0
	v_mov_b32_e32 v117, v0
	v_mov_b32_e32 v118, v0
	v_mov_b32_e32 v119, v0
	v_mov_b32_e32 v120, v0
	v_mov_b32_e32 v121, v0
	v_mov_b32_e32 v72, v0
	v_mov_b32_e32 v73, v0
	v_mov_b32_e32 v74, v0
	v_mov_b32_e32 v75, v0
	v_mov_b32_e32 v76, v0
	v_mov_b32_e32 v77, v0
	v_mov_b32_e32 v78, v0
	v_mov_b32_e32 v79, v0
	v_mov_b32_e32 v88, v0
	v_mov_b32_e32 v89, v0
	v_mov_b32_e32 v90, v0
	v_mov_b32_e32 v91, v0
	v_mov_b32_e32 v92, v0
	v_mov_b32_e32 v93, v0
	v_mov_b32_e32 v94, v0
	v_mov_b32_e32 v95, v0
	v_mov_b32_e32 v106, v0
	v_mov_b32_e32 v107, v0
	v_mov_b32_e32 v108, v0
	v_mov_b32_e32 v109, v0
	v_mov_b32_e32 v110, v0
	v_mov_b32_e32 v111, v0
	v_mov_b32_e32 v112, v0
	v_mov_b32_e32 v113, v0
	v_mov_b32_e32 v122, v0
	v_mov_b32_e32 v123, v0
	v_mov_b32_e32 v124, v0
	v_mov_b32_e32 v125, v0
	v_mov_b32_e32 v126, v0
	v_mov_b32_e32 v127, v0
	v_mov_b32_e32 v128, v0
	v_mov_b32_e32 v129, v0
	s_mov_b64 s[4:5], 0x80
	.p2alignl 6, 3212836864

; __device__ __forceinline__ void filter_item(const Params& p, int l, int Lf, int t0, float* dst, float* hidT  , int wid0) {
;     ...
; #pragma unroll 16
;     for (int j = 0; j < 64; ++j) {
;         const float wa = w3[j * 1024 + tid], wb = w3[j * 1024 + 512 + tid];
.LBB0_719:
	s_waitcnt vmcnt(0)
	v_add_u32_e32 v182, 0xffffc200, v4
	v_ashrrev_i32_e32 v183, 31, v182
	v_lshl_add_u64 v[182:183], v[182:183], 2, s[72:73]
	s_mov_b64 vcc, 0x1000
	global_load_dword v174, v[182:183], off
	global_load_dword v176, v[182:183], off offset:2048
	v_lshl_add_u64 v[182:183], v[182:183], 0, vcc
	global_load_dword v178, v[182:183], off
	global_load_dword v180, v[182:183], off offset:2048
	v_lshl_add_u64 v[182:183], v[182:183], 0, vcc
	s_add_i32 s1, s0, 0x1b800
	v_mov_b32_e32 v186, s1
	ds_read_b128 v[110:113], v186
	ds_read_b128 v[114:117], v186 offset:16
	ds_read_b128 v[118:121], v186 offset:32
	ds_read_b128 v[122:125], v186 offset:48
	ds_read_b128 v[126:129], v186 offset:64
	ds_read_b128 v[130:133], v186 offset:80
	ds_read_b128 v[134:137], v186 offset:96
	ds_read_b128 v[138:141], v186 offset:112
	s_movk_i32 s1, 31
	.p2alignl 6, 3212836864
